# speedup vs baseline: 1.0035x; 1.0035x over previous
; DEV void gemm_tile(const u16* __restrict__ A, const u16* __restrict__ Bt, u16* __restrict__ C, int N, int K,
;                    int brow, int bcol, unsigned char* smem, int epi, const GateEpi& ge) {
;     ...
;     const int pm = brow >> 8, pn = bcol >> 8;
;     float w0[2], w1[2], w2[2], bs[2];
; #pragma unroll
;     for (int n = 0; n < 2; ++n) {
;       const int cg = pn * 128 + wc * 32 + n * 16 + fr2;
;       w0[n] = ge.cw[cg]; w1[n] = ge.cw[DFF + cg]; w2[n] = ge.cw[2 * DFF + cg]; bs[n] = ge.cb[cg];
;     }
;     ...
;   u16* Cw = C + (size_t)(brow + wr * 64) * N + bcol + wc * 32;
; #pragma unroll
;   for (int ai = 0; ai < 2; ++ai)
; #pragma unroll
;     for (int bj = 0; bj < 2; ++bj)
; #pragma unroll
;       for (int m = 0; m < 4; ++m)
; #pragma unroll
;         for (int n = 0; n < 2; ++n)
; #pragma unroll
;           for (int j = 0; j < 4; ++j)
;             Cw[(size_t)(ai * 128 + m * 16 + fq2 * 4 + j) * N + (bj * 128 + n * 16 + fr2)] = f2bf(acc[ai][bj][m][n][j]);
.Lg_epi:
	v_readfirstlane_b32 s0, v160
	s_andn2_b32 s0, s0, 63
	s_andn2_b64 vcc, exec, s[2:3]
	v_or_b32_e32 v180, s0, v161
	s_nop 0
	v_bfe_u32 v181, v180, 4, 2
	v_and_b32_e32 v180, 15, v180
	s_cbranch_vccz .Lg_gate
	s_add_i32 s0, s51, s49
	s_mul_hi_u32 s1, s0, s44
	s_mul_i32 s0, s0, s44
	s_lshl_b64 s[0:1], s[0:1], 1
	s_add_u32 s0, s14, s0
	s_addc_u32 s1, s15, s1
	s_lshl_b64 s[4:5], s[92:93], 1
	s_add_u32 s0, s0, s4
	s_addc_u32 s1, s1, s5
	s_lshl_b32 s4, s50, 6
	s_add_u32 s0, s0, s4
	s_addc_u32 s1, s1, 0
	v_mul_u32_u24_e32 v153, s44, v180
	v_lshlrev_b32_e32 v153, 1, v153
	v_lshl_add_u32 v153, v181, 4, v153
	s_lshl_b32 s4, s44, 5
	s_lshl_b32 s5, s44, 7
	v_cvt_pk_bf16_f32 v184, v124, v125
	v_cvt_pk_bf16_f32 v185, v126, v127
	v_cvt_pk_bf16_f32 v186, v120, v121
	v_cvt_pk_bf16_f32 v187, v122, v123
	global_store_dwordx4 v153, v[184:187], s[0:1] nt
	v_cvt_pk_bf16_f32 v188, v84, v85
	v_cvt_pk_bf16_f32 v189, v86, v87
	v_cvt_pk_bf16_f32 v190, v68, v69
	v_cvt_pk_bf16_f32 v191, v70, v71
	global_store_dwordx4 v153, v[188:191], s[0:1] offset:256 nt
	s_add_u32 s0, s0, s4
	s_addc_u32 s1, s1, 0
	v_cvt_pk_bf16_f32 v192, v116, v117
	v_cvt_pk_bf16_f32 v193, v118, v119
	v_cvt_pk_bf16_f32 v194, v112, v113
	v_cvt_pk_bf16_f32 v195, v114, v115
	global_store_dwordx4 v153, v[192:195], s[0:1] nt
	v_cvt_pk_bf16_f32 v196, v52, v53
	v_cvt_pk_bf16_f32 v197, v54, v55
	v_cvt_pk_bf16_f32 v198, v48, v49
	v_cvt_pk_bf16_f32 v199, v50, v51
	global_store_dwordx4 v153, v[196:199], s[0:1] offset:256 nt
	s_add_u32 s0, s0, s4
	s_addc_u32 s1, s1, 0
	v_cvt_pk_bf16_f32 v184, v108, v109
	v_cvt_pk_bf16_f32 v185, v110, v111
	v_cvt_pk_bf16_f32 v186, v104, v105
	v_cvt_pk_bf16_f32 v187, v106, v107
	global_store_dwordx4 v153, v[184:187], s[0:1] nt
	v_cvt_pk_bf16_f32 v188, v44, v45
	v_cvt_pk_bf16_f32 v189, v46, v47
	v_cvt_pk_bf16_f32 v190, v40, v41
	v_cvt_pk_bf16_f32 v191, v42, v43
	global_store_dwordx4 v153, v[188:191], s[0:1] offset:256 nt
	s_add_u32 s0, s0, s4
	s_addc_u32 s1, s1, 0
	v_cvt_pk_bf16_f32 v192, v100, v101
	v_cvt_pk_bf16_f32 v193, v102, v103
	v_cvt_pk_bf16_f32 v194, v96, v97
	v_cvt_pk_bf16_f32 v195, v98, v99
	global_store_dwordx4 v153, v[192:195], s[0:1] nt
	v_cvt_pk_bf16_f32 v196, v36, v37
	v_cvt_pk_bf16_f32 v197, v38, v39
	v_cvt_pk_bf16_f32 v198, v32, v33
	v_cvt_pk_bf16_f32 v199, v34, v35
	global_store_dwordx4 v153, v[196:199], s[0:1] offset:256 nt
	s_add_u32 s0, s0, s4
	s_addc_u32 s1, s1, 0
	s_add_u32 s0, s0, s5
	s_addc_u32 s1, s1, 0
	v_cvt_pk_bf16_f32 v184, v28, v29
	v_cvt_pk_bf16_f32 v185, v30, v31
	v_cvt_pk_bf16_f32 v186, v24, v25
	v_cvt_pk_bf16_f32 v187, v26, v27
	global_store_dwordx4 v153, v[184:187], s[0:1] nt
	v_cvt_pk_bf16_f32 v188, v56, v57
	v_cvt_pk_bf16_f32 v189, v58, v59
	v_cvt_pk_bf16_f32 v190, v60, v61
	v_cvt_pk_bf16_f32 v191, v62, v63
	global_store_dwordx4 v153, v[188:191], s[0:1] offset:256 nt
	s_add_u32 s0, s0, s4
	s_addc_u32 s1, s1, 0
	v_cvt_pk_bf16_f32 v192, v20, v21
	v_cvt_pk_bf16_f32 v193, v22, v23
	v_cvt_pk_bf16_f32 v194, v16, v17
	v_cvt_pk_bf16_f32 v195, v18, v19
	global_store_dwordx4 v153, v[192:195], s[0:1] nt
	v_cvt_pk_bf16_f32 v196, v64, v65
	v_cvt_pk_bf16_f32 v197, v66, v67
	v_cvt_pk_bf16_f32 v198, v72, v73
	v_cvt_pk_bf16_f32 v199, v74, v75
	global_store_dwordx4 v153, v[196:199], s[0:1] offset:256 nt
	s_add_u32 s0, s0, s4
	s_addc_u32 s1, s1, 0
	v_cvt_pk_bf16_f32 v184, v12, v13
	v_cvt_pk_bf16_f32 v185, v14, v15
	v_cvt_pk_bf16_f32 v186, v8, v9
	v_cvt_pk_bf16_f32 v187, v10, v11
	global_store_dwordx4 v153, v[184:187], s[0:1] nt
	v_cvt_pk_bf16_f32 v188, v76, v77
	v_cvt_pk_bf16_f32 v189, v78, v79
	v_cvt_pk_bf16_f32 v190, v80, v81
	v_cvt_pk_bf16_f32 v191, v82, v83
	global_store_dwordx4 v153, v[188:191], s[0:1] offset:256 nt
	s_add_u32 s0, s0, s4
	s_addc_u32 s1, s1, 0
	v_cvt_pk_bf16_f32 v192, v4, v5
	v_cvt_pk_bf16_f32 v193, v6, v7
	v_cvt_pk_bf16_f32 v194, v0, v1
	v_cvt_pk_bf16_f32 v195, v2, v3
	global_store_dwordx4 v153, v[192:195], s[0:1] nt
	v_cvt_pk_bf16_f32 v196, v88, v89
	v_cvt_pk_bf16_f32 v197, v90, v91
	v_cvt_pk_bf16_f32 v198, v92, v93
	v_cvt_pk_bf16_f32 v199, v94, v95
	global_store_dwordx4 v153, v[196:199], s[0:1] offset:256 nt
	s_branch .Lg_post
.Lg_gate:
	s_add_i32 s62, s1, 0x21000
	v_lshlrev_b32_e32 v154, 5, v181
	v_add_u32_e32 v154, s62, v154
	ds_read_b128 v[184:187], v154 offset:0
	ds_read_b128 v[188:191], v154 offset:16
	ds_read_b128 v[192:195], v154 offset:128
	ds_read_b128 v[196:199], v154 offset:144
	ds_read_b128 v[200:203], v154 offset:256
	ds_read_b128 v[204:207], v154 offset:272
	ds_read_b128 v[208:211], v154 offset:384
	ds_read_b128 v[212:215], v154 offset:400
	s_lshl_b32 s0, s47, 5
	s_and_b32 s0, s0, 0xffffff00
	s_lshl_b32 s1, s50, 6
	s_add_i32 s28, s0, s1
	s_add_i32 s0, s51, s49
	s_mul_hi_u32 s1, s0, s85
	s_mul_i32 s0, s0, s85
	s_add_u32 s0, s0, s28
	s_addc_u32 s1, s1, 0
	s_add_u32 s0, s80, s0
	s_addc_u32 s1, s81, s1
	s_ashr_i32 s4, s49, 8
	s_mul_i32 s4, s4, 0x5800
	s_add_i32 s4, s4, s28
	s_add_u32 s6, s22, s4
	s_addc_u32 s7, s23, 0
	s_add_u32 s54, s82, s4
	s_addc_u32 s55, s83, 0
	s_sub_u32 s54, s54, 0x26800
	s_subb_u32 s55, s55, 0
	s_add_u32 s4, s20, s4
	s_addc_u32 s5, s21, 0
	v_mul_u32_u24_e32 v153, 0x2c00, v180
	v_lshl_add_u32 v153, v181, 4, v153
	v_and_b32_e32 v157, 1, v180
	v_lshlrev_b32_e32 v157, 5, v157
	v_lshl_add_u32 v157, v181, 6, v157
	s_lshl_b32 s62, s50, 8
	s_add_i32 s62, s62, 0x20000
	v_add_u32_e32 v157, s62, v157
	s_lshl_b32 s62, s34, 10
	v_add_u32_e32 v158, s62, v157
	s_add_i32 s62, s34, 3
	s_and_b32 s62, s62, 3
	s_lshl_b32 s62, s62, 10
	v_add_u32_e32 v159, s62, v157
	s_mov_b32 s52, 0xbdd2d3e8
	s_mov_b32 s53, 0xbdd2d3e8
	s_mov_b32 s94, 1.0
	s_mov_b32 s95, 1.0
	s_mov_b32 exec_lo, 0xc000c000
	s_mov_b32 exec_hi, 0xc000c000
	ds_write_b128 v158, v[100:103]
	ds_write_b128 v158, v[96:99] offset:16
	ds_write_b128 v158, v[4:7] offset:2048
	ds_write_b128 v158, v[0:3] offset:2064
	s_mov_b64 exec, -1
	s_waitcnt lgkmcnt(0)
	s_barrier
; DEV float bf2f(u16 h) { return __uint_as_float(((uint32_t)h) << 16); }
; DEV float gelu_tanh(float x) {
;   const float e = __builtin_amdgcn_exp2f(x * __builtin_fmaf(x * x, -0.10294324f, -2.3022082f));
;   return x * __builtin_amdgcn_rcpf(1.0f + e);
; }
; DEV void gemm_tile(const u16* __restrict__ A, const u16* __restrict__ Bt, u16* __restrict__ C, int N, int K,
;                    int brow, int bcol, unsigned char* smem, int epi, const GateEpi& ge) {
;     ...
;         const int R0 = ai * 128 + wr * 64 + m * 16 + fq2 * 4;
; #pragma unroll
;         for (int n = 0; n < 2; ++n) {
;           const int cl = wc * 32 + n * 16 + fr2, cg = pn * 128 + cl;
;           float am2 = 0.f, am1 = 0.f;
;           if (R0 > 0) { am2 = bf2f(sAt[(R0 - 2) * AS + cl]); am1 = bf2f(sAt[(R0 - 1) * AS + cl]); }
; #pragma unroll
;           for (int j = 0; j < 4; ++j) {
;             const float a0 = acc[ai][0][m][n][j], b0 = acc[ai][1][m][n][j];
;             if (R0 > 0 || j >= 2) {
;               const float gv = gelu_tanh(bs[n] + w0[n] * am2 + w1[n] * am1 + w2[n] * a0) * b0;
;               ge.g[(size_t)(brow + R0 + j) * DFF + cg] = f2bf(gv);
;             } else {
;               ge.first_a[((size_t)pm * 2 + j) * DFF + cg] = sAt[(R0 + j) * AS + cl];
;               ge.first_b[((size_t)pm * 2 + j) * DFF + cg] = f2bf(b0);
;             }
;             if (R0 == 252 && j >= 2) ge.halo_a[((size_t)pm * 2 + (j - 2)) * DFF + cg] = sAt[(R0 + j) * AS + cl];
;             am2 = am1; am1 = a0;
	ds_read_b128 v[232:235], v159
	ds_read_b128 v[236:239], v159 offset:16
	s_add_i32 s62, s34, 1
	s_lshl_b32 s62, s62, 10
	v_add_u32_e32 v156, s62, v157
	v_cmp_eq_u32_e32 vcc, 0, v180
	s_nop 1
	v_cndmask_b32_e32 v216, 0, v192, vcc
	v_cndmask_b32_e32 v217, 0, v193, vcc
	v_cndmask_b32_e32 v218, 0, v194, vcc
	v_cndmask_b32_e32 v219, 0, v195, vcc
	v_cndmask_b32_e32 v220, 0, v196, vcc
	v_cndmask_b32_e32 v221, 0, v197, vcc
	v_cndmask_b32_e32 v222, 0, v198, vcc
	v_cndmask_b32_e32 v223, 0, v199, vcc
	v_cmp_gt_u32_e32 vcc, 2, v180
	s_nop 1
	v_cndmask_b32_e32 v224, 0, v184, vcc
	v_cndmask_b32_e32 v225, 0, v185, vcc
	v_cndmask_b32_e32 v226, 0, v186, vcc
	v_cndmask_b32_e32 v227, 0, v187, vcc
	v_cndmask_b32_e32 v228, 0, v188, vcc
	v_cndmask_b32_e32 v229, 0, v189, vcc
	v_cndmask_b32_e32 v230, 0, v190, vcc
	v_cndmask_b32_e32 v231, 0, v191, vcc
	v_mov_b32_e32 v180, v163
	v_mov_b32_e32 v181, v163
	s_waitcnt lgkmcnt(0)
	v_pk_fma_f32 v[240:241], v[200:201], v[124:125], v[208:209]
	v_pk_fma_f32 v[242:243], v[202:203], v[126:127], v[210:211]
	v_pk_fma_f32 v[244:245], v[204:205], v[120:121], v[212:213]
	v_pk_fma_f32 v[246:247], v[206:207], v[122:123], v[214:215]
	v_fmac_f32_dpp v240, v124, v192 row_shr:1 row_mask:0xf bank_mask:0xf
	v_fmac_f32_dpp v241, v125, v193 row_shr:1 row_mask:0xf bank_mask:0xf
	v_fmac_f32_dpp v242, v126, v194 row_shr:1 row_mask:0xf bank_mask:0xf
	v_fmac_f32_dpp v243, v127, v195 row_shr:1 row_mask:0xf bank_mask:0xf
	v_fmac_f32_dpp v244, v120, v196 row_shr:1 row_mask:0xf bank_mask:0xf
	v_fmac_f32_dpp v245, v121, v197 row_shr:1 row_mask:0xf bank_mask:0xf
	v_fmac_f32_dpp v246, v122, v198 row_shr:1 row_mask:0xf bank_mask:0xf
	v_fmac_f32_dpp v247, v123, v199 row_shr:1 row_mask:0xf bank_mask:0xf
	v_fmac_f32_dpp v240, v232, v216 row_ror:1 row_mask:0xf bank_mask:0xf
	v_fmac_f32_dpp v241, v233, v217 row_ror:1 row_mask:0xf bank_mask:0xf
	v_fmac_f32_dpp v242, v234, v218 row_ror:1 row_mask:0xf bank_mask:0xf
	v_fmac_f32_dpp v243, v235, v219 row_ror:1 row_mask:0xf bank_mask:0xf
	v_fmac_f32_dpp v244, v236, v220 row_ror:1 row_mask:0xf bank_mask:0xf
	v_fmac_f32_dpp v245, v237, v221 row_ror:1 row_mask:0xf bank_mask:0xf
	v_fmac_f32_dpp v246, v238, v222 row_ror:1 row_mask:0xf bank_mask:0xf
	v_fmac_f32_dpp v247, v239, v223 row_ror:1 row_mask:0xf bank_mask:0xf
	v_fmac_f32_dpp v240, v124, v184 row_shr:2 row_mask:0xf bank_mask:0xf
	v_fmac_f32_dpp v241, v125, v185 row_shr:2 row_mask:0xf bank_mask:0xf
	v_fmac_f32_dpp v242, v126, v186 row_shr:2 row_mask:0xf bank_mask:0xf
	v_fmac_f32_dpp v243, v127, v187 row_shr:2 row_mask:0xf bank_mask:0xf
	v_fmac_f32_dpp v244, v120, v188 row_shr:2 row_mask:0xf bank_mask:0xf
	v_fmac_f32_dpp v245, v121, v189 row_shr:2 row_mask:0xf bank_mask:0xf
	v_fmac_f32_dpp v246, v122, v190 row_shr:2 row_mask:0xf bank_mask:0xf
	v_fmac_f32_dpp v247, v123, v191 row_shr:2 row_mask:0xf bank_mask:0xf
	v_fmac_f32_dpp v240, v232, v224 row_ror:2 row_mask:0xf bank_mask:0xf
	v_fmac_f32_dpp v241, v233, v225 row_ror:2 row_mask:0xf bank_mask:0xf
	v_fmac_f32_dpp v242, v234, v226 row_ror:2 row_mask:0xf bank_mask:0xf
	v_fmac_f32_dpp v243, v235, v227 row_ror:2 row_mask:0xf bank_mask:0xf
	v_fmac_f32_dpp v244, v236, v228 row_ror:2 row_mask:0xf bank_mask:0xf
	v_fmac_f32_dpp v245, v237, v229 row_ror:2 row_mask:0xf bank_mask:0xf
	v_fmac_f32_dpp v246, v238, v230 row_ror:2 row_mask:0xf bank_mask:0xf
	v_fmac_f32_dpp v247, v239, v231 row_ror:2 row_mask:0xf bank_mask:0xf
	ds_read_b128 v[232:235], v156
	ds_read_b128 v[236:239], v156 offset:16
	v_pk_mul_f32 v[248:249], v[240:241], v[240:241]
	v_pk_mul_f32 v[250:251], v[242:243], v[242:243]
	v_pk_mul_f32 v[182:183], v[244:245], v[244:245]
	v_pk_mul_f32 v[154:155], v[246:247], v[246:247]
	v_pk_fma_f32 v[248:249], v[248:249], s[52:53], v[180:181]
	v_pk_fma_f32 v[250:251], v[250:251], s[52:53], v[180:181]
	v_pk_fma_f32 v[182:183], v[182:183], s[52:53], v[180:181]
	v_pk_fma_f32 v[154:155], v[154:155], s[52:53], v[180:181]
	v_pk_mul_f32 v[248:249], v[240:241], v[248:249]
	v_pk_mul_f32 v[250:251], v[242:243], v[250:251]
	v_pk_mul_f32 v[182:183], v[244:245], v[182:183]
	v_pk_mul_f32 v[154:155], v[246:247], v[154:155]
	v_exp_f32_e32 v248, v248
	v_exp_f32_e32 v249, v249
	v_exp_f32_e32 v250, v250
	v_exp_f32_e32 v251, v251
	v_exp_f32_e32 v182, v182
	v_exp_f32_e32 v183, v183
	v_exp_f32_e32 v154, v154
	v_exp_f32_e32 v155, v155
	v_pk_add_f32 v[248:249], v[248:249], s[94:95]
	v_pk_add_f32 v[250:251], v[250:251], s[94:95]
	v_pk_add_f32 v[182:183], v[182:183], s[94:95]
	v_pk_add_f32 v[154:155], v[154:155], s[94:95]
	v_rcp_f32_e32 v248, v248
	v_rcp_f32_e32 v249, v249
	v_rcp_f32_e32 v250, v250
	v_rcp_f32_e32 v251, v251
	v_rcp_f32_e32 v182, v182
	v_rcp_f32_e32 v183, v183
	v_rcp_f32_e32 v154, v154
	v_rcp_f32_e32 v155, v155
	v_pk_mul_f32 v[240:241], v[240:241], v[248:249]
	v_pk_mul_f32 v[242:243], v[242:243], v[250:251]
	v_pk_mul_f32 v[244:245], v[244:245], v[182:183]
	v_pk_mul_f32 v[246:247], v[246:247], v[154:155]
	v_pk_mul_f32 v[240:241], v[240:241], v[84:85]
	v_pk_mul_f32 v[242:243], v[242:243], v[86:87]
	v_pk_mul_f32 v[244:245], v[244:245], v[68:69]
	v_pk_mul_f32 v[246:247], v[246:247], v[70:71]
	v_cvt_pk_bf16_f32 v248, v240, v241
	v_cvt_pk_bf16_f32 v249, v242, v243
	v_cvt_pk_bf16_f32 v250, v244, v245
	v_cvt_pk_bf16_f32 v251, v246, v247
	s_cmp_lg_u32 s34, 0
	s_cbranch_scc1 .Lgate_plain00_0
	s_mov_b32 exec_lo, 0x30003
	s_mov_b32 exec_hi, 0x30003
	v_cvt_pk_bf16_f32 v240, v124, v125
	v_cvt_pk_bf16_f32 v241, v126, v127
	v_cvt_pk_bf16_f32 v242, v120, v121
	v_cvt_pk_bf16_f32 v243, v122, v123
	v_cvt_pk_bf16_f32 v244, v84, v85
	v_cvt_pk_bf16_f32 v245, v86, v87
	v_cvt_pk_bf16_f32 v246, v68, v69
	v_cvt_pk_bf16_f32 v247, v70, v71
	global_store_dwordx4 v153, v[240:243], s[4:5] nt
	global_store_dwordx4 v153, v[244:247], s[6:7] nt
	s_not_b64 exec, exec
	global_store_dwordx4 v153, v[248:251], s[0:1] nt
	s_mov_b64 exec, -1
	s_branch .Lgate_done00_0
; DEV float bf2f(u16 h) { return __uint_as_float(((uint32_t)h) << 16); }
; DEV float gelu_tanh(float x) {
;   const float e = __builtin_amdgcn_exp2f(x * __builtin_fmaf(x * x, -0.10294324f, -2.3022082f));
;   return x * __builtin_amdgcn_rcpf(1.0f + e);
; }
; DEV void gemm_tile(const u16* __restrict__ A, const u16* __restrict__ Bt, u16* __restrict__ C, int N, int K,
;                    int brow, int bcol, unsigned char* smem, int epi, const GateEpi& ge) {
;     ...
;         const int R0 = ai * 128 + wr * 64 + m * 16 + fq2 * 4;
; #pragma unroll
;         for (int n = 0; n < 2; ++n) {
;           const int cl = wc * 32 + n * 16 + fr2, cg = pn * 128 + cl;
;           float am2 = 0.f, am1 = 0.f;
;           if (R0 > 0) { am2 = bf2f(sAt[(R0 - 2) * AS + cl]); am1 = bf2f(sAt[(R0 - 1) * AS + cl]); }
; #pragma unroll
;           for (int j = 0; j < 4; ++j) {
;             const float a0 = acc[ai][0][m][n][j], b0 = acc[ai][1][m][n][j];
;             if (R0 > 0 || j >= 2) {
;               const float gv = gelu_tanh(bs[n] + w0[n] * am2 + w1[n] * am1 + w2[n] * a0) * b0;
;               ge.g[(size_t)(brow + R0 + j) * DFF + cg] = f2bf(gv);
;             } else {
;               ge.first_a[((size_t)pm * 2 + j) * DFF + cg] = sAt[(R0 + j) * AS + cl];
;               ge.first_b[((size_t)pm * 2 + j) * DFF + cg] = f2bf(b0);
;             }
;             if (R0 == 252 && j >= 2) ge.halo_a[((size_t)pm * 2 + (j - 2)) * DFF + cg] = sAt[(R0 + j) * AS + cl];
;             am2 = am1; am1 = a0;
.Lgate_plain00_0:
	global_store_dwordx4 v153, v[248:251], s[0:1] nt
.Lgate_done00_0:
	s_add_u32 s0, s0, 0x2c000
	s_addc_u32 s1, s1, 0
	v_pk_fma_f32 v[240:241], v[200:201], v[116:117], v[208:209]
	v_pk_fma_f32 v[242:243], v[202:203], v[118:119], v[210:211]
	v_pk_fma_f32 v[244:245], v[204:205], v[112:113], v[212:213]
	v_pk_fma_f32 v[246:247], v[206:207], v[114:115], v[214:215]
	v_fmac_f32_dpp v240, v116, v192 row_shr:1 row_mask:0xf bank_mask:0xf
	v_fmac_f32_dpp v241, v117, v193 row_shr:1 row_mask:0xf bank_mask:0xf
	v_fmac_f32_dpp v242, v118, v194 row_shr:1 row_mask:0xf bank_mask:0xf
	v_fmac_f32_dpp v243, v119, v195 row_shr:1 row_mask:0xf bank_mask:0xf
	v_fmac_f32_dpp v244, v112, v196 row_shr:1 row_mask:0xf bank_mask:0xf
	v_fmac_f32_dpp v245, v113, v197 row_shr:1 row_mask:0xf bank_mask:0xf
	v_fmac_f32_dpp v246, v114, v198 row_shr:1 row_mask:0xf bank_mask:0xf
	v_fmac_f32_dpp v247, v115, v199 row_shr:1 row_mask:0xf bank_mask:0xf
	v_fmac_f32_dpp v240, v124, v216 row_ror:1 row_mask:0xf bank_mask:0xf
	v_fmac_f32_dpp v241, v125, v217 row_ror:1 row_mask:0xf bank_mask:0xf
	v_fmac_f32_dpp v242, v126, v218 row_ror:1 row_mask:0xf bank_mask:0xf
	v_fmac_f32_dpp v243, v127, v219 row_ror:1 row_mask:0xf bank_mask:0xf
	v_fmac_f32_dpp v244, v120, v220 row_ror:1 row_mask:0xf bank_mask:0xf
	v_fmac_f32_dpp v245, v121, v221 row_ror:1 row_mask:0xf bank_mask:0xf
	v_fmac_f32_dpp v246, v122, v222 row_ror:1 row_mask:0xf bank_mask:0xf
	v_fmac_f32_dpp v247, v123, v223 row_ror:1 row_mask:0xf bank_mask:0xf
	v_fmac_f32_dpp v240, v116, v184 row_shr:2 row_mask:0xf bank_mask:0xf
	v_fmac_f32_dpp v241, v117, v185 row_shr:2 row_mask:0xf bank_mask:0xf
	v_fmac_f32_dpp v242, v118, v186 row_shr:2 row_mask:0xf bank_mask:0xf
	v_fmac_f32_dpp v243, v119, v187 row_shr:2 row_mask:0xf bank_mask:0xf
	v_fmac_f32_dpp v244, v112, v188 row_shr:2 row_mask:0xf bank_mask:0xf
	v_fmac_f32_dpp v245, v113, v189 row_shr:2 row_mask:0xf bank_mask:0xf
	v_fmac_f32_dpp v246, v114, v190 row_shr:2 row_mask:0xf bank_mask:0xf
	v_fmac_f32_dpp v247, v115, v191 row_shr:2 row_mask:0xf bank_mask:0xf
	v_fmac_f32_dpp v240, v124, v224 row_ror:2 row_mask:0xf bank_mask:0xf
	v_fmac_f32_dpp v241, v125, v225 row_ror:2 row_mask:0xf bank_mask:0xf
	v_fmac_f32_dpp v242, v126, v226 row_ror:2 row_mask:0xf bank_mask:0xf
	v_fmac_f32_dpp v243, v127, v227 row_ror:2 row_mask:0xf bank_mask:0xf
	v_fmac_f32_dpp v244, v120, v228 row_ror:2 row_mask:0xf bank_mask:0xf
	v_fmac_f32_dpp v245, v121, v229 row_ror:2 row_mask:0xf bank_mask:0xf
	v_fmac_f32_dpp v246, v122, v230 row_ror:2 row_mask:0xf bank_mask:0xf
	v_fmac_f32_dpp v247, v123, v231 row_ror:2 row_mask:0xf bank_mask:0xf
	v_pk_mul_f32 v[248:249], v[240:241], v[240:241]
	v_pk_mul_f32 v[250:251], v[242:243], v[242:243]
	v_pk_mul_f32 v[182:183], v[244:245], v[244:245]
	v_pk_mul_f32 v[154:155], v[246:247], v[246:247]
	v_pk_fma_f32 v[248:249], v[248:249], s[52:53], v[180:181]
	v_pk_fma_f32 v[250:251], v[250:251], s[52:53], v[180:181]
	v_pk_fma_f32 v[182:183], v[182:183], s[52:53], v[180:181]
	v_pk_fma_f32 v[154:155], v[154:155], s[52:53], v[180:181]
	v_pk_mul_f32 v[248:249], v[240:241], v[248:249]
	v_pk_mul_f32 v[250:251], v[242:243], v[250:251]
	v_pk_mul_f32 v[182:183], v[244:245], v[182:183]
	v_pk_mul_f32 v[154:155], v[246:247], v[154:155]
	v_exp_f32_e32 v248, v248
	v_exp_f32_e32 v249, v249
	v_exp_f32_e32 v250, v250
	v_exp_f32_e32 v251, v251
	v_exp_f32_e32 v182, v182
	v_exp_f32_e32 v183, v183
	v_exp_f32_e32 v154, v154
	v_exp_f32_e32 v155, v155
	v_pk_add_f32 v[248:249], v[248:249], s[94:95]
	v_pk_add_f32 v[250:251], v[250:251], s[94:95]
	v_pk_add_f32 v[182:183], v[182:183], s[94:95]
	v_pk_add_f32 v[154:155], v[154:155], s[94:95]
	v_rcp_f32_e32 v248, v248
	v_rcp_f32_e32 v249, v249
	v_rcp_f32_e32 v250, v250
	v_rcp_f32_e32 v251, v251
	v_rcp_f32_e32 v182, v182
	v_rcp_f32_e32 v183, v183
	v_rcp_f32_e32 v154, v154
	v_rcp_f32_e32 v155, v155
	v_pk_mul_f32 v[240:241], v[240:241], v[248:249]
	v_pk_mul_f32 v[242:243], v[242:243], v[250:251]
	v_pk_mul_f32 v[244:245], v[244:245], v[182:183]
	v_pk_mul_f32 v[246:247], v[246:247], v[154:155]
	v_pk_mul_f32 v[240:241], v[240:241], v[52:53]
	v_pk_mul_f32 v[242:243], v[242:243], v[54:55]
	v_pk_mul_f32 v[244:245], v[244:245], v[48:49]
	v_pk_mul_f32 v[246:247], v[246:247], v[50:51]
	v_cvt_pk_bf16_f32 v248, v240, v241
	v_cvt_pk_bf16_f32 v249, v242, v243
	v_cvt_pk_bf16_f32 v250, v244, v245
	v_cvt_pk_bf16_f32 v251, v246, v247
	global_store_dwordx4 v153, v[248:251], s[0:1] nt
	s_add_u32 s0, s0, 0x2c000
	s_addc_u32 s1, s1, 0
	v_pk_fma_f32 v[240:241], v[200:201], v[108:109], v[208:209]
	v_pk_fma_f32 v[242:243], v[202:203], v[110:111], v[210:211]
	v_pk_fma_f32 v[244:245], v[204:205], v[104:105], v[212:213]
	v_pk_fma_f32 v[246:247], v[206:207], v[106:107], v[214:215]
	v_fmac_f32_dpp v240, v108, v192 row_shr:1 row_mask:0xf bank_mask:0xf
	v_fmac_f32_dpp v241, v109, v193 row_shr:1 row_mask:0xf bank_mask:0xf
	v_fmac_f32_dpp v242, v110, v194 row_shr:1 row_mask:0xf bank_mask:0xf
	v_fmac_f32_dpp v243, v111, v195 row_shr:1 row_mask:0xf bank_mask:0xf
	v_fmac_f32_dpp v244, v104, v196 row_shr:1 row_mask:0xf bank_mask:0xf
	v_fmac_f32_dpp v245, v105, v197 row_shr:1 row_mask:0xf bank_mask:0xf
	v_fmac_f32_dpp v246, v106, v198 row_shr:1 row_mask:0xf bank_mask:0xf
	v_fmac_f32_dpp v247, v107, v199 row_shr:1 row_mask:0xf bank_mask:0xf
	v_fmac_f32_dpp v240, v116, v216 row_ror:1 row_mask:0xf bank_mask:0xf
	v_fmac_f32_dpp v241, v117, v217 row_ror:1 row_mask:0xf bank_mask:0xf
	v_fmac_f32_dpp v242, v118, v218 row_ror:1 row_mask:0xf bank_mask:0xf
	v_fmac_f32_dpp v243, v119, v219 row_ror:1 row_mask:0xf bank_mask:0xf
	v_fmac_f32_dpp v244, v112, v220 row_ror:1 row_mask:0xf bank_mask:0xf
; DEV float bf2f(u16 h) { return __uint_as_float(((uint32_t)h) << 16); }
; DEV float gelu_tanh(float x) {
;   const float e = __builtin_amdgcn_exp2f(x * __builtin_fmaf(x * x, -0.10294324f, -2.3022082f));
;   return x * __builtin_amdgcn_rcpf(1.0f + e);
; }
; DEV void gemm_tile(const u16* __restrict__ A, const u16* __restrict__ Bt, u16* __restrict__ C, int N, int K,
;                    int brow, int bcol, unsigned char* smem, int epi, const GateEpi& ge) {
;     ...
;         const int R0 = ai * 128 + wr * 64 + m * 16 + fq2 * 4;
; #pragma unroll
;         for (int n = 0; n < 2; ++n) {
;           const int cl = wc * 32 + n * 16 + fr2, cg = pn * 128 + cl;
;           float am2 = 0.f, am1 = 0.f;
;           if (R0 > 0) { am2 = bf2f(sAt[(R0 - 2) * AS + cl]); am1 = bf2f(sAt[(R0 - 1) * AS + cl]); }
; #pragma unroll
;           for (int j = 0; j < 4; ++j) {
;             const float a0 = acc[ai][0][m][n][j], b0 = acc[ai][1][m][n][j];
;             if (R0 > 0 || j >= 2) {
;               const float gv = gelu_tanh(bs[n] + w0[n] * am2 + w1[n] * am1 + w2[n] * a0) * b0;
;               ge.g[(size_t)(brow + R0 + j) * DFF + cg] = f2bf(gv);
;             } else {
;               ge.first_a[((size_t)pm * 2 + j) * DFF + cg] = sAt[(R0 + j) * AS + cl];
;               ge.first_b[((size_t)pm * 2 + j) * DFF + cg] = f2bf(b0);
;             }
;             if (R0 == 252 && j >= 2) ge.halo_a[((size_t)pm * 2 + (j - 2)) * DFF + cg] = sAt[(R0 + j) * AS + cl];
;             am2 = am1; am1 = a0;
	v_fmac_f32_dpp v245, v113, v221 row_ror:1 row_mask:0xf bank_mask:0xf
	v_fmac_f32_dpp v246, v114, v222 row_ror:1 row_mask:0xf bank_mask:0xf
	v_fmac_f32_dpp v247, v115, v223 row_ror:1 row_mask:0xf bank_mask:0xf
	v_fmac_f32_dpp v240, v108, v184 row_shr:2 row_mask:0xf bank_mask:0xf
	v_fmac_f32_dpp v241, v109, v185 row_shr:2 row_mask:0xf bank_mask:0xf
	v_fmac_f32_dpp v242, v110, v186 row_shr:2 row_mask:0xf bank_mask:0xf
	v_fmac_f32_dpp v243, v111, v187 row_shr:2 row_mask:0xf bank_mask:0xf
	v_fmac_f32_dpp v244, v104, v188 row_shr:2 row_mask:0xf bank_mask:0xf
	v_fmac_f32_dpp v245, v105, v189 row_shr:2 row_mask:0xf bank_mask:0xf
	v_fmac_f32_dpp v246, v106, v190 row_shr:2 row_mask:0xf bank_mask:0xf
	v_fmac_f32_dpp v247, v107, v191 row_shr:2 row_mask:0xf bank_mask:0xf
	v_fmac_f32_dpp v240, v116, v224 row_ror:2 row_mask:0xf bank_mask:0xf
	v_fmac_f32_dpp v241, v117, v225 row_ror:2 row_mask:0xf bank_mask:0xf
	v_fmac_f32_dpp v242, v118, v226 row_ror:2 row_mask:0xf bank_mask:0xf
	v_fmac_f32_dpp v243, v119, v227 row_ror:2 row_mask:0xf bank_mask:0xf
	v_fmac_f32_dpp v244, v112, v228 row_ror:2 row_mask:0xf bank_mask:0xf
	v_fmac_f32_dpp v245, v113, v229 row_ror:2 row_mask:0xf bank_mask:0xf
	v_fmac_f32_dpp v246, v114, v230 row_ror:2 row_mask:0xf bank_mask:0xf
	v_fmac_f32_dpp v247, v115, v231 row_ror:2 row_mask:0xf bank_mask:0xf
	v_pk_mul_f32 v[248:249], v[240:241], v[240:241]
	v_pk_mul_f32 v[250:251], v[242:243], v[242:243]
	v_pk_mul_f32 v[182:183], v[244:245], v[244:245]
	v_pk_mul_f32 v[154:155], v[246:247], v[246:247]
	v_pk_fma_f32 v[248:249], v[248:249], s[52:53], v[180:181]
	v_pk_fma_f32 v[250:251], v[250:251], s[52:53], v[180:181]
	v_pk_fma_f32 v[182:183], v[182:183], s[52:53], v[180:181]
	v_pk_fma_f32 v[154:155], v[154:155], s[52:53], v[180:181]
	v_pk_mul_f32 v[248:249], v[240:241], v[248:249]
	v_pk_mul_f32 v[250:251], v[242:243], v[250:251]
	v_pk_mul_f32 v[182:183], v[244:245], v[182:183]
	v_pk_mul_f32 v[154:155], v[246:247], v[154:155]
	v_exp_f32_e32 v248, v248
	v_exp_f32_e32 v249, v249
	v_exp_f32_e32 v250, v250
	v_exp_f32_e32 v251, v251
	v_exp_f32_e32 v182, v182
	v_exp_f32_e32 v183, v183
	v_exp_f32_e32 v154, v154
	v_exp_f32_e32 v155, v155
	v_pk_add_f32 v[248:249], v[248:249], s[94:95]
	v_pk_add_f32 v[250:251], v[250:251], s[94:95]
	v_pk_add_f32 v[182:183], v[182:183], s[94:95]
	v_pk_add_f32 v[154:155], v[154:155], s[94:95]
	v_rcp_f32_e32 v248, v248
	v_rcp_f32_e32 v249, v249
	v_rcp_f32_e32 v250, v250
	v_rcp_f32_e32 v251, v251
	v_rcp_f32_e32 v182, v182
	v_rcp_f32_e32 v183, v183
	v_rcp_f32_e32 v154, v154
	v_rcp_f32_e32 v155, v155
	v_pk_mul_f32 v[240:241], v[240:241], v[248:249]
	v_pk_mul_f32 v[242:243], v[242:243], v[250:251]
	v_pk_mul_f32 v[244:245], v[244:245], v[182:183]
	v_pk_mul_f32 v[246:247], v[246:247], v[154:155]
	v_pk_mul_f32 v[240:241], v[240:241], v[44:45]
	v_pk_mul_f32 v[242:243], v[242:243], v[46:47]
	v_pk_mul_f32 v[244:245], v[244:245], v[40:41]
	v_pk_mul_f32 v[246:247], v[246:247], v[42:43]
	v_cvt_pk_bf16_f32 v248, v240, v241
	v_cvt_pk_bf16_f32 v249, v242, v243
	v_cvt_pk_bf16_f32 v250, v244, v245
	v_cvt_pk_bf16_f32 v251, v246, v247
	global_store_dwordx4 v153, v[248:251], s[0:1] nt
	s_add_u32 s0, s0, 0x2c000
	s_addc_u32 s1, s1, 0
	v_pk_fma_f32 v[240:241], v[200:201], v[100:101], v[208:209]
	v_pk_fma_f32 v[242:243], v[202:203], v[102:103], v[210:211]
	v_pk_fma_f32 v[244:245], v[204:205], v[96:97], v[212:213]
	v_pk_fma_f32 v[246:247], v[206:207], v[98:99], v[214:215]
	v_fmac_f32_dpp v240, v100, v192 row_shr:1 row_mask:0xf bank_mask:0xf
	v_fmac_f32_dpp v241, v101, v193 row_shr:1 row_mask:0xf bank_mask:0xf
	v_fmac_f32_dpp v242, v102, v194 row_shr:1 row_mask:0xf bank_mask:0xf
	v_fmac_f32_dpp v243, v103, v195 row_shr:1 row_mask:0xf bank_mask:0xf
	v_fmac_f32_dpp v244, v96, v196 row_shr:1 row_mask:0xf bank_mask:0xf
	v_fmac_f32_dpp v245, v97, v197 row_shr:1 row_mask:0xf bank_mask:0xf
	v_fmac_f32_dpp v246, v98, v198 row_shr:1 row_mask:0xf bank_mask:0xf
	v_fmac_f32_dpp v247, v99, v199 row_shr:1 row_mask:0xf bank_mask:0xf
	v_fmac_f32_dpp v240, v108, v216 row_ror:1 row_mask:0xf bank_mask:0xf
	v_fmac_f32_dpp v241, v109, v217 row_ror:1 row_mask:0xf bank_mask:0xf
	v_fmac_f32_dpp v242, v110, v218 row_ror:1 row_mask:0xf bank_mask:0xf
	v_fmac_f32_dpp v243, v111, v219 row_ror:1 row_mask:0xf bank_mask:0xf
	v_fmac_f32_dpp v244, v104, v220 row_ror:1 row_mask:0xf bank_mask:0xf
	v_fmac_f32_dpp v245, v105, v221 row_ror:1 row_mask:0xf bank_mask:0xf
	v_fmac_f32_dpp v246, v106, v222 row_ror:1 row_mask:0xf bank_mask:0xf
	v_fmac_f32_dpp v247, v107, v223 row_ror:1 row_mask:0xf bank_mask:0xf
	v_fmac_f32_dpp v240, v100, v184 row_shr:2 row_mask:0xf bank_mask:0xf
	v_fmac_f32_dpp v241, v101, v185 row_shr:2 row_mask:0xf bank_mask:0xf
	v_fmac_f32_dpp v242, v102, v186 row_shr:2 row_mask:0xf bank_mask:0xf
	v_fmac_f32_dpp v243, v103, v187 row_shr:2 row_mask:0xf bank_mask:0xf
	v_fmac_f32_dpp v244, v96, v188 row_shr:2 row_mask:0xf bank_mask:0xf
	v_fmac_f32_dpp v245, v97, v189 row_shr:2 row_mask:0xf bank_mask:0xf
	v_fmac_f32_dpp v246, v98, v190 row_shr:2 row_mask:0xf bank_mask:0xf
	v_fmac_f32_dpp v247, v99, v191 row_shr:2 row_mask:0xf bank_mask:0xf
	v_fmac_f32_dpp v240, v108, v224 row_ror:2 row_mask:0xf bank_mask:0xf
	v_fmac_f32_dpp v241, v109, v225 row_ror:2 row_mask:0xf bank_mask:0xf
	v_fmac_f32_dpp v242, v110, v226 row_ror:2 row_mask:0xf bank_mask:0xf
	v_fmac_f32_dpp v243, v111, v227 row_ror:2 row_mask:0xf bank_mask:0xf
	v_fmac_f32_dpp v244, v104, v228 row_ror:2 row_mask:0xf bank_mask:0xf
	v_fmac_f32_dpp v245, v105, v229 row_ror:2 row_mask:0xf bank_mask:0xf
	v_fmac_f32_dpp v246, v106, v230 row_ror:2 row_mask:0xf bank_mask:0xf
	v_fmac_f32_dpp v247, v107, v231 row_ror:2 row_mask:0xf bank_mask:0xf
; DEV float bf2f(u16 h) { return __uint_as_float(((uint32_t)h) << 16); }
; DEV float gelu_tanh(float x) {
;   const float e = __builtin_amdgcn_exp2f(x * __builtin_fmaf(x * x, -0.10294324f, -2.3022082f));
;   return x * __builtin_amdgcn_rcpf(1.0f + e);
; }
; DEV void gemm_tile(const u16* __restrict__ A, const u16* __restrict__ Bt, u16* __restrict__ C, int N, int K,
;                    int brow, int bcol, unsigned char* smem, int epi, const GateEpi& ge) {
;     ...
;         const int R0 = ai * 128 + wr * 64 + m * 16 + fq2 * 4;
; #pragma unroll
;         for (int n = 0; n < 2; ++n) {
;           const int cl = wc * 32 + n * 16 + fr2, cg = pn * 128 + cl;
;           float am2 = 0.f, am1 = 0.f;
;           if (R0 > 0) { am2 = bf2f(sAt[(R0 - 2) * AS + cl]); am1 = bf2f(sAt[(R0 - 1) * AS + cl]); }
; #pragma unroll
;           for (int j = 0; j < 4; ++j) {
;             const float a0 = acc[ai][0][m][n][j], b0 = acc[ai][1][m][n][j];
;             if (R0 > 0 || j >= 2) {
;               const float gv = gelu_tanh(bs[n] + w0[n] * am2 + w1[n] * am1 + w2[n] * a0) * b0;
;               ge.g[(size_t)(brow + R0 + j) * DFF + cg] = f2bf(gv);
;             } else {
;               ge.first_a[((size_t)pm * 2 + j) * DFF + cg] = sAt[(R0 + j) * AS + cl];
;               ge.first_b[((size_t)pm * 2 + j) * DFF + cg] = f2bf(b0);
;             }
;             if (R0 == 252 && j >= 2) ge.halo_a[((size_t)pm * 2 + (j - 2)) * DFF + cg] = sAt[(R0 + j) * AS + cl];
;             am2 = am1; am1 = a0;
	v_pk_mul_f32 v[248:249], v[240:241], v[240:241]
	v_pk_mul_f32 v[250:251], v[242:243], v[242:243]
	v_pk_mul_f32 v[182:183], v[244:245], v[244:245]
	v_pk_mul_f32 v[154:155], v[246:247], v[246:247]
	v_pk_fma_f32 v[248:249], v[248:249], s[52:53], v[180:181]
	v_pk_fma_f32 v[250:251], v[250:251], s[52:53], v[180:181]
	v_pk_fma_f32 v[182:183], v[182:183], s[52:53], v[180:181]
	v_pk_fma_f32 v[154:155], v[154:155], s[52:53], v[180:181]
	v_pk_mul_f32 v[248:249], v[240:241], v[248:249]
	v_pk_mul_f32 v[250:251], v[242:243], v[250:251]
	v_pk_mul_f32 v[182:183], v[244:245], v[182:183]
	v_pk_mul_f32 v[154:155], v[246:247], v[154:155]
	v_exp_f32_e32 v248, v248
	v_exp_f32_e32 v249, v249
	v_exp_f32_e32 v250, v250
	v_exp_f32_e32 v251, v251
	v_exp_f32_e32 v182, v182
	v_exp_f32_e32 v183, v183
	v_exp_f32_e32 v154, v154
	v_exp_f32_e32 v155, v155
	v_pk_add_f32 v[248:249], v[248:249], s[94:95]
	v_pk_add_f32 v[250:251], v[250:251], s[94:95]
	v_pk_add_f32 v[182:183], v[182:183], s[94:95]
	v_pk_add_f32 v[154:155], v[154:155], s[94:95]
	v_rcp_f32_e32 v248, v248
	v_rcp_f32_e32 v249, v249
	v_rcp_f32_e32 v250, v250
	v_rcp_f32_e32 v251, v251
	v_rcp_f32_e32 v182, v182
	v_rcp_f32_e32 v183, v183
	v_rcp_f32_e32 v154, v154
	v_rcp_f32_e32 v155, v155
	v_pk_mul_f32 v[240:241], v[240:241], v[248:249]
	v_pk_mul_f32 v[242:243], v[242:243], v[250:251]
	v_pk_mul_f32 v[244:245], v[244:245], v[182:183]
	v_pk_mul_f32 v[246:247], v[246:247], v[154:155]
	v_pk_mul_f32 v[240:241], v[240:241], v[36:37]
	v_pk_mul_f32 v[242:243], v[242:243], v[38:39]
	v_pk_mul_f32 v[244:245], v[244:245], v[32:33]
	v_pk_mul_f32 v[246:247], v[246:247], v[34:35]
	v_cvt_pk_bf16_f32 v248, v240, v241
	v_cvt_pk_bf16_f32 v249, v242, v243
	v_cvt_pk_bf16_f32 v250, v244, v245
	v_cvt_pk_bf16_f32 v251, v246, v247
	global_store_dwordx4 v153, v[248:251], s[0:1] nt
	s_add_u32 s0, s0, 0xdc000
	s_addc_u32 s1, s1, 0
	s_waitcnt lgkmcnt(0)
	v_pk_fma_f32 v[240:241], v[200:201], v[28:29], v[208:209]
	v_pk_fma_f32 v[242:243], v[202:203], v[30:31], v[210:211]
	v_pk_fma_f32 v[244:245], v[204:205], v[24:25], v[212:213]
	v_pk_fma_f32 v[246:247], v[206:207], v[26:27], v[214:215]
	v_fmac_f32_dpp v240, v28, v192 row_shr:1 row_mask:0xf bank_mask:0xf
	v_fmac_f32_dpp v241, v29, v193 row_shr:1 row_mask:0xf bank_mask:0xf
	v_fmac_f32_dpp v242, v30, v194 row_shr:1 row_mask:0xf bank_mask:0xf
	v_fmac_f32_dpp v243, v31, v195 row_shr:1 row_mask:0xf bank_mask:0xf
	v_fmac_f32_dpp v244, v24, v196 row_shr:1 row_mask:0xf bank_mask:0xf
	v_fmac_f32_dpp v245, v25, v197 row_shr:1 row_mask:0xf bank_mask:0xf
	v_fmac_f32_dpp v246, v26, v198 row_shr:1 row_mask:0xf bank_mask:0xf
	v_fmac_f32_dpp v247, v27, v199 row_shr:1 row_mask:0xf bank_mask:0xf
	v_fmac_f32_dpp v240, v232, v216 row_ror:1 row_mask:0xf bank_mask:0xf
	v_fmac_f32_dpp v241, v233, v217 row_ror:1 row_mask:0xf bank_mask:0xf
	v_fmac_f32_dpp v242, v234, v218 row_ror:1 row_mask:0xf bank_mask:0xf
	v_fmac_f32_dpp v243, v235, v219 row_ror:1 row_mask:0xf bank_mask:0xf
	v_fmac_f32_dpp v244, v236, v220 row_ror:1 row_mask:0xf bank_mask:0xf
	v_fmac_f32_dpp v245, v237, v221 row_ror:1 row_mask:0xf bank_mask:0xf
	v_fmac_f32_dpp v246, v238, v222 row_ror:1 row_mask:0xf bank_mask:0xf
	v_fmac_f32_dpp v247, v239, v223 row_ror:1 row_mask:0xf bank_mask:0xf
	v_fmac_f32_dpp v240, v28, v184 row_shr:2 row_mask:0xf bank_mask:0xf
	v_fmac_f32_dpp v241, v29, v185 row_shr:2 row_mask:0xf bank_mask:0xf
	v_fmac_f32_dpp v242, v30, v186 row_shr:2 row_mask:0xf bank_mask:0xf
	v_fmac_f32_dpp v243, v31, v187 row_shr:2 row_mask:0xf bank_mask:0xf
	v_fmac_f32_dpp v244, v24, v188 row_shr:2 row_mask:0xf bank_mask:0xf
	v_fmac_f32_dpp v245, v25, v189 row_shr:2 row_mask:0xf bank_mask:0xf
	v_fmac_f32_dpp v246, v26, v190 row_shr:2 row_mask:0xf bank_mask:0xf
	v_fmac_f32_dpp v247, v27, v191 row_shr:2 row_mask:0xf bank_mask:0xf
	v_fmac_f32_dpp v240, v232, v224 row_ror:2 row_mask:0xf bank_mask:0xf
	v_fmac_f32_dpp v241, v233, v225 row_ror:2 row_mask:0xf bank_mask:0xf
	v_fmac_f32_dpp v242, v234, v226 row_ror:2 row_mask:0xf bank_mask:0xf
	v_fmac_f32_dpp v243, v235, v227 row_ror:2 row_mask:0xf bank_mask:0xf
	v_fmac_f32_dpp v244, v236, v228 row_ror:2 row_mask:0xf bank_mask:0xf
	v_fmac_f32_dpp v245, v237, v229 row_ror:2 row_mask:0xf bank_mask:0xf
	v_fmac_f32_dpp v246, v238, v230 row_ror:2 row_mask:0xf bank_mask:0xf
	v_fmac_f32_dpp v247, v239, v231 row_ror:2 row_mask:0xf bank_mask:0xf
	v_pk_mul_f32 v[248:249], v[240:241], v[240:241]
	v_pk_mul_f32 v[250:251], v[242:243], v[242:243]
	v_pk_mul_f32 v[182:183], v[244:245], v[244:245]
	v_pk_mul_f32 v[154:155], v[246:247], v[246:247]
	v_pk_fma_f32 v[248:249], v[248:249], s[52:53], v[180:181]
	v_pk_fma_f32 v[250:251], v[250:251], s[52:53], v[180:181]
	v_pk_fma_f32 v[182:183], v[182:183], s[52:53], v[180:181]
	v_pk_fma_f32 v[154:155], v[154:155], s[52:53], v[180:181]
	v_pk_mul_f32 v[248:249], v[240:241], v[248:249]
	v_pk_mul_f32 v[250:251], v[242:243], v[250:251]
	v_pk_mul_f32 v[182:183], v[244:245], v[182:183]
	v_pk_mul_f32 v[154:155], v[246:247], v[154:155]
	v_exp_f32_e32 v248, v248
	v_exp_f32_e32 v249, v249
	v_exp_f32_e32 v250, v250
	v_exp_f32_e32 v251, v251
	v_exp_f32_e32 v182, v182
	v_exp_f32_e32 v183, v183
	v_exp_f32_e32 v154, v154
	v_exp_f32_e32 v155, v155
	v_pk_add_f32 v[248:249], v[248:249], s[94:95]
	v_pk_add_f32 v[250:251], v[250:251], s[94:95]
	v_pk_add_f32 v[182:183], v[182:183], s[94:95]
	v_pk_add_f32 v[154:155], v[154:155], s[94:95]
	v_rcp_f32_e32 v248, v248
	v_rcp_f32_e32 v249, v249
	v_rcp_f32_e32 v250, v250
	v_rcp_f32_e32 v251, v251
	v_rcp_f32_e32 v182, v182
	v_rcp_f32_e32 v183, v183
	v_rcp_f32_e32 v154, v154
	v_rcp_f32_e32 v155, v155
	v_pk_mul_f32 v[240:241], v[240:241], v[248:249]
; DEV float bf2f(u16 h) { return __uint_as_float(((uint32_t)h) << 16); }
; DEV float gelu_tanh(float x) {
;   const float e = __builtin_amdgcn_exp2f(x * __builtin_fmaf(x * x, -0.10294324f, -2.3022082f));
;   return x * __builtin_amdgcn_rcpf(1.0f + e);
; }
; DEV void gemm_tile(const u16* __restrict__ A, const u16* __restrict__ Bt, u16* __restrict__ C, int N, int K,
;                    int brow, int bcol, unsigned char* smem, int epi, const GateEpi& ge) {
;     ...
;         const int R0 = ai * 128 + wr * 64 + m * 16 + fq2 * 4;
; #pragma unroll
;         for (int n = 0; n < 2; ++n) {
;           const int cl = wc * 32 + n * 16 + fr2, cg = pn * 128 + cl;
;           float am2 = 0.f, am1 = 0.f;
;           if (R0 > 0) { am2 = bf2f(sAt[(R0 - 2) * AS + cl]); am1 = bf2f(sAt[(R0 - 1) * AS + cl]); }
; #pragma unroll
;           for (int j = 0; j < 4; ++j) {
;             const float a0 = acc[ai][0][m][n][j], b0 = acc[ai][1][m][n][j];
;             if (R0 > 0 || j >= 2) {
;               const float gv = gelu_tanh(bs[n] + w0[n] * am2 + w1[n] * am1 + w2[n] * a0) * b0;
;               ge.g[(size_t)(brow + R0 + j) * DFF + cg] = f2bf(gv);
;             } else {
;               ge.first_a[((size_t)pm * 2 + j) * DFF + cg] = sAt[(R0 + j) * AS + cl];
;               ge.first_b[((size_t)pm * 2 + j) * DFF + cg] = f2bf(b0);
;             }
;             if (R0 == 252 && j >= 2) ge.halo_a[((size_t)pm * 2 + (j - 2)) * DFF + cg] = sAt[(R0 + j) * AS + cl];
;             am2 = am1; am1 = a0;
	v_pk_mul_f32 v[242:243], v[242:243], v[250:251]
	v_pk_mul_f32 v[244:245], v[244:245], v[182:183]
	v_pk_mul_f32 v[246:247], v[246:247], v[154:155]
	v_pk_mul_f32 v[240:241], v[240:241], v[56:57]
	v_pk_mul_f32 v[242:243], v[242:243], v[58:59]
	v_pk_mul_f32 v[244:245], v[244:245], v[60:61]
	v_pk_mul_f32 v[246:247], v[246:247], v[62:63]
	v_cvt_pk_bf16_f32 v248, v240, v241
	v_cvt_pk_bf16_f32 v249, v242, v243
	v_cvt_pk_bf16_f32 v250, v244, v245
	v_cvt_pk_bf16_f32 v251, v246, v247
	global_store_dwordx4 v153, v[248:251], s[0:1] nt
	s_add_u32 s0, s0, 0x2c000
	s_addc_u32 s1, s1, 0
	v_pk_fma_f32 v[240:241], v[200:201], v[20:21], v[208:209]
	v_pk_fma_f32 v[242:243], v[202:203], v[22:23], v[210:211]
	v_pk_fma_f32 v[244:245], v[204:205], v[16:17], v[212:213]
	v_pk_fma_f32 v[246:247], v[206:207], v[18:19], v[214:215]
	v_fmac_f32_dpp v240, v20, v192 row_shr:1 row_mask:0xf bank_mask:0xf
	v_fmac_f32_dpp v241, v21, v193 row_shr:1 row_mask:0xf bank_mask:0xf
	v_fmac_f32_dpp v242, v22, v194 row_shr:1 row_mask:0xf bank_mask:0xf
	v_fmac_f32_dpp v243, v23, v195 row_shr:1 row_mask:0xf bank_mask:0xf
	v_fmac_f32_dpp v244, v16, v196 row_shr:1 row_mask:0xf bank_mask:0xf
	v_fmac_f32_dpp v245, v17, v197 row_shr:1 row_mask:0xf bank_mask:0xf
	v_fmac_f32_dpp v246, v18, v198 row_shr:1 row_mask:0xf bank_mask:0xf
	v_fmac_f32_dpp v247, v19, v199 row_shr:1 row_mask:0xf bank_mask:0xf
	v_fmac_f32_dpp v240, v28, v216 row_ror:1 row_mask:0xf bank_mask:0xf
	v_fmac_f32_dpp v241, v29, v217 row_ror:1 row_mask:0xf bank_mask:0xf
	v_fmac_f32_dpp v242, v30, v218 row_ror:1 row_mask:0xf bank_mask:0xf
	v_fmac_f32_dpp v243, v31, v219 row_ror:1 row_mask:0xf bank_mask:0xf
	v_fmac_f32_dpp v244, v24, v220 row_ror:1 row_mask:0xf bank_mask:0xf
	v_fmac_f32_dpp v245, v25, v221 row_ror:1 row_mask:0xf bank_mask:0xf
	v_fmac_f32_dpp v246, v26, v222 row_ror:1 row_mask:0xf bank_mask:0xf
	v_fmac_f32_dpp v247, v27, v223 row_ror:1 row_mask:0xf bank_mask:0xf
	v_fmac_f32_dpp v240, v20, v184 row_shr:2 row_mask:0xf bank_mask:0xf
	v_fmac_f32_dpp v241, v21, v185 row_shr:2 row_mask:0xf bank_mask:0xf
	v_fmac_f32_dpp v242, v22, v186 row_shr:2 row_mask:0xf bank_mask:0xf
	v_fmac_f32_dpp v243, v23, v187 row_shr:2 row_mask:0xf bank_mask:0xf
	v_fmac_f32_dpp v244, v16, v188 row_shr:2 row_mask:0xf bank_mask:0xf
	v_fmac_f32_dpp v245, v17, v189 row_shr:2 row_mask:0xf bank_mask:0xf
	v_fmac_f32_dpp v246, v18, v190 row_shr:2 row_mask:0xf bank_mask:0xf
	v_fmac_f32_dpp v247, v19, v191 row_shr:2 row_mask:0xf bank_mask:0xf
	v_fmac_f32_dpp v240, v28, v224 row_ror:2 row_mask:0xf bank_mask:0xf
	v_fmac_f32_dpp v241, v29, v225 row_ror:2 row_mask:0xf bank_mask:0xf
	v_fmac_f32_dpp v242, v30, v226 row_ror:2 row_mask:0xf bank_mask:0xf
	v_fmac_f32_dpp v243, v31, v227 row_ror:2 row_mask:0xf bank_mask:0xf
	v_fmac_f32_dpp v244, v24, v228 row_ror:2 row_mask:0xf bank_mask:0xf
	v_fmac_f32_dpp v245, v25, v229 row_ror:2 row_mask:0xf bank_mask:0xf
	v_fmac_f32_dpp v246, v26, v230 row_ror:2 row_mask:0xf bank_mask:0xf
	v_fmac_f32_dpp v247, v27, v231 row_ror:2 row_mask:0xf bank_mask:0xf
	v_pk_mul_f32 v[248:249], v[240:241], v[240:241]
	v_pk_mul_f32 v[250:251], v[242:243], v[242:243]
	v_pk_mul_f32 v[182:183], v[244:245], v[244:245]
	v_pk_mul_f32 v[154:155], v[246:247], v[246:247]
	v_pk_fma_f32 v[248:249], v[248:249], s[52:53], v[180:181]
	v_pk_fma_f32 v[250:251], v[250:251], s[52:53], v[180:181]
	v_pk_fma_f32 v[182:183], v[182:183], s[52:53], v[180:181]
	v_pk_fma_f32 v[154:155], v[154:155], s[52:53], v[180:181]
	v_pk_mul_f32 v[248:249], v[240:241], v[248:249]
	v_pk_mul_f32 v[250:251], v[242:243], v[250:251]
	v_pk_mul_f32 v[182:183], v[244:245], v[182:183]
	v_pk_mul_f32 v[154:155], v[246:247], v[154:155]
	v_exp_f32_e32 v248, v248
	v_exp_f32_e32 v249, v249
	v_exp_f32_e32 v250, v250
	v_exp_f32_e32 v251, v251
	v_exp_f32_e32 v182, v182
	v_exp_f32_e32 v183, v183
	v_exp_f32_e32 v154, v154
	v_exp_f32_e32 v155, v155
	v_pk_add_f32 v[248:249], v[248:249], s[94:95]
	v_pk_add_f32 v[250:251], v[250:251], s[94:95]
	v_pk_add_f32 v[182:183], v[182:183], s[94:95]
	v_pk_add_f32 v[154:155], v[154:155], s[94:95]
	v_rcp_f32_e32 v248, v248
	v_rcp_f32_e32 v249, v249
	v_rcp_f32_e32 v250, v250
	v_rcp_f32_e32 v251, v251
	v_rcp_f32_e32 v182, v182
	v_rcp_f32_e32 v183, v183
	v_rcp_f32_e32 v154, v154
	v_rcp_f32_e32 v155, v155
	v_pk_mul_f32 v[240:241], v[240:241], v[248:249]
	v_pk_mul_f32 v[242:243], v[242:243], v[250:251]
	v_pk_mul_f32 v[244:245], v[244:245], v[182:183]
	v_pk_mul_f32 v[246:247], v[246:247], v[154:155]
	v_pk_mul_f32 v[240:241], v[240:241], v[64:65]
	v_pk_mul_f32 v[242:243], v[242:243], v[66:67]
	v_pk_mul_f32 v[244:245], v[244:245], v[72:73]
	v_pk_mul_f32 v[246:247], v[246:247], v[74:75]
	v_cvt_pk_bf16_f32 v248, v240, v241
	v_cvt_pk_bf16_f32 v249, v242, v243
	v_cvt_pk_bf16_f32 v250, v244, v245
	v_cvt_pk_bf16_f32 v251, v246, v247
	global_store_dwordx4 v153, v[248:251], s[0:1] nt
	s_add_u32 s0, s0, 0x2c000
	s_addc_u32 s1, s1, 0
	v_pk_fma_f32 v[240:241], v[200:201], v[12:13], v[208:209]
	v_pk_fma_f32 v[242:243], v[202:203], v[14:15], v[210:211]
	v_pk_fma_f32 v[244:245], v[204:205], v[8:9], v[212:213]
	v_pk_fma_f32 v[246:247], v[206:207], v[10:11], v[214:215]
	v_fmac_f32_dpp v240, v12, v192 row_shr:1 row_mask:0xf bank_mask:0xf
	v_fmac_f32_dpp v241, v13, v193 row_shr:1 row_mask:0xf bank_mask:0xf
	v_fmac_f32_dpp v242, v14, v194 row_shr:1 row_mask:0xf bank_mask:0xf
	v_fmac_f32_dpp v243, v15, v195 row_shr:1 row_mask:0xf bank_mask:0xf
	v_fmac_f32_dpp v244, v8, v196 row_shr:1 row_mask:0xf bank_mask:0xf
	v_fmac_f32_dpp v245, v9, v197 row_shr:1 row_mask:0xf bank_mask:0xf
	v_fmac_f32_dpp v246, v10, v198 row_shr:1 row_mask:0xf bank_mask:0xf
	v_fmac_f32_dpp v247, v11, v199 row_shr:1 row_mask:0xf bank_mask:0xf
; DEV float bf2f(u16 h) { return __uint_as_float(((uint32_t)h) << 16); }
; DEV float gelu_tanh(float x) {
;   const float e = __builtin_amdgcn_exp2f(x * __builtin_fmaf(x * x, -0.10294324f, -2.3022082f));
;   return x * __builtin_amdgcn_rcpf(1.0f + e);
; }
; DEV void gemm_tile(const u16* __restrict__ A, const u16* __restrict__ Bt, u16* __restrict__ C, int N, int K,
;                    int brow, int bcol, unsigned char* smem, int epi, const GateEpi& ge) {
;     ...
;         const int R0 = ai * 128 + wr * 64 + m * 16 + fq2 * 4;
; #pragma unroll
;         for (int n = 0; n < 2; ++n) {
;           const int cl = wc * 32 + n * 16 + fr2, cg = pn * 128 + cl;
;           float am2 = 0.f, am1 = 0.f;
;           if (R0 > 0) { am2 = bf2f(sAt[(R0 - 2) * AS + cl]); am1 = bf2f(sAt[(R0 - 1) * AS + cl]); }
; #pragma unroll
;           for (int j = 0; j < 4; ++j) {
;             const float a0 = acc[ai][0][m][n][j], b0 = acc[ai][1][m][n][j];
;             if (R0 > 0 || j >= 2) {
;               const float gv = gelu_tanh(bs[n] + w0[n] * am2 + w1[n] * am1 + w2[n] * a0) * b0;
;               ge.g[(size_t)(brow + R0 + j) * DFF + cg] = f2bf(gv);
;             } else {
;               ge.first_a[((size_t)pm * 2 + j) * DFF + cg] = sAt[(R0 + j) * AS + cl];
;               ge.first_b[((size_t)pm * 2 + j) * DFF + cg] = f2bf(b0);
;             }
;             if (R0 == 252 && j >= 2) ge.halo_a[((size_t)pm * 2 + (j - 2)) * DFF + cg] = sAt[(R0 + j) * AS + cl];
;             am2 = am1; am1 = a0;
	v_fmac_f32_dpp v240, v20, v216 row_ror:1 row_mask:0xf bank_mask:0xf
	v_fmac_f32_dpp v241, v21, v217 row_ror:1 row_mask:0xf bank_mask:0xf
	v_fmac_f32_dpp v242, v22, v218 row_ror:1 row_mask:0xf bank_mask:0xf
	v_fmac_f32_dpp v243, v23, v219 row_ror:1 row_mask:0xf bank_mask:0xf
	v_fmac_f32_dpp v244, v16, v220 row_ror:1 row_mask:0xf bank_mask:0xf
	v_fmac_f32_dpp v245, v17, v221 row_ror:1 row_mask:0xf bank_mask:0xf
	v_fmac_f32_dpp v246, v18, v222 row_ror:1 row_mask:0xf bank_mask:0xf
	v_fmac_f32_dpp v247, v19, v223 row_ror:1 row_mask:0xf bank_mask:0xf
	v_fmac_f32_dpp v240, v12, v184 row_shr:2 row_mask:0xf bank_mask:0xf
	v_fmac_f32_dpp v241, v13, v185 row_shr:2 row_mask:0xf bank_mask:0xf
	v_fmac_f32_dpp v242, v14, v186 row_shr:2 row_mask:0xf bank_mask:0xf
	v_fmac_f32_dpp v243, v15, v187 row_shr:2 row_mask:0xf bank_mask:0xf
	v_fmac_f32_dpp v244, v8, v188 row_shr:2 row_mask:0xf bank_mask:0xf
	v_fmac_f32_dpp v245, v9, v189 row_shr:2 row_mask:0xf bank_mask:0xf
	v_fmac_f32_dpp v246, v10, v190 row_shr:2 row_mask:0xf bank_mask:0xf
	v_fmac_f32_dpp v247, v11, v191 row_shr:2 row_mask:0xf bank_mask:0xf
	v_fmac_f32_dpp v240, v20, v224 row_ror:2 row_mask:0xf bank_mask:0xf
	v_fmac_f32_dpp v241, v21, v225 row_ror:2 row_mask:0xf bank_mask:0xf
	v_fmac_f32_dpp v242, v22, v226 row_ror:2 row_mask:0xf bank_mask:0xf
	v_fmac_f32_dpp v243, v23, v227 row_ror:2 row_mask:0xf bank_mask:0xf
	v_fmac_f32_dpp v244, v16, v228 row_ror:2 row_mask:0xf bank_mask:0xf
	v_fmac_f32_dpp v245, v17, v229 row_ror:2 row_mask:0xf bank_mask:0xf
	v_fmac_f32_dpp v246, v18, v230 row_ror:2 row_mask:0xf bank_mask:0xf
	v_fmac_f32_dpp v247, v19, v231 row_ror:2 row_mask:0xf bank_mask:0xf
	v_pk_mul_f32 v[248:249], v[240:241], v[240:241]
	v_pk_mul_f32 v[250:251], v[242:243], v[242:243]
	v_pk_mul_f32 v[182:183], v[244:245], v[244:245]
	v_pk_mul_f32 v[154:155], v[246:247], v[246:247]
	v_pk_fma_f32 v[248:249], v[248:249], s[52:53], v[180:181]
	v_pk_fma_f32 v[250:251], v[250:251], s[52:53], v[180:181]
	v_pk_fma_f32 v[182:183], v[182:183], s[52:53], v[180:181]
	v_pk_fma_f32 v[154:155], v[154:155], s[52:53], v[180:181]
	v_pk_mul_f32 v[248:249], v[240:241], v[248:249]
	v_pk_mul_f32 v[250:251], v[242:243], v[250:251]
	v_pk_mul_f32 v[182:183], v[244:245], v[182:183]
	v_pk_mul_f32 v[154:155], v[246:247], v[154:155]
	v_exp_f32_e32 v248, v248
	v_exp_f32_e32 v249, v249
	v_exp_f32_e32 v250, v250
	v_exp_f32_e32 v251, v251
	v_exp_f32_e32 v182, v182
	v_exp_f32_e32 v183, v183
	v_exp_f32_e32 v154, v154
	v_exp_f32_e32 v155, v155
	v_pk_add_f32 v[248:249], v[248:249], s[94:95]
	v_pk_add_f32 v[250:251], v[250:251], s[94:95]
	v_pk_add_f32 v[182:183], v[182:183], s[94:95]
	v_pk_add_f32 v[154:155], v[154:155], s[94:95]
	v_rcp_f32_e32 v248, v248
	v_rcp_f32_e32 v249, v249
	v_rcp_f32_e32 v250, v250
	v_rcp_f32_e32 v251, v251
	v_rcp_f32_e32 v182, v182
	v_rcp_f32_e32 v183, v183
	v_rcp_f32_e32 v154, v154
	v_rcp_f32_e32 v155, v155
	v_pk_mul_f32 v[240:241], v[240:241], v[248:249]
	v_pk_mul_f32 v[242:243], v[242:243], v[250:251]
	v_pk_mul_f32 v[244:245], v[244:245], v[182:183]
	v_pk_mul_f32 v[246:247], v[246:247], v[154:155]
	v_pk_mul_f32 v[240:241], v[240:241], v[76:77]
	v_pk_mul_f32 v[242:243], v[242:243], v[78:79]
	v_pk_mul_f32 v[244:245], v[244:245], v[80:81]
	v_pk_mul_f32 v[246:247], v[246:247], v[82:83]
	v_cvt_pk_bf16_f32 v248, v240, v241
	v_cvt_pk_bf16_f32 v249, v242, v243
	v_cvt_pk_bf16_f32 v250, v244, v245
	v_cvt_pk_bf16_f32 v251, v246, v247
	global_store_dwordx4 v153, v[248:251], s[0:1] nt
	s_add_u32 s0, s0, 0x2c000
	s_addc_u32 s1, s1, 0
	v_pk_fma_f32 v[240:241], v[200:201], v[4:5], v[208:209]
	v_pk_fma_f32 v[242:243], v[202:203], v[6:7], v[210:211]
	v_pk_fma_f32 v[244:245], v[204:205], v[0:1], v[212:213]
	v_pk_fma_f32 v[246:247], v[206:207], v[2:3], v[214:215]
	v_fmac_f32_dpp v240, v4, v192 row_shr:1 row_mask:0xf bank_mask:0xf
	v_fmac_f32_dpp v241, v5, v193 row_shr:1 row_mask:0xf bank_mask:0xf
	v_fmac_f32_dpp v242, v6, v194 row_shr:1 row_mask:0xf bank_mask:0xf
	v_fmac_f32_dpp v243, v7, v195 row_shr:1 row_mask:0xf bank_mask:0xf
; DEV float bf2f(u16 h) { return __uint_as_float(((uint32_t)h) << 16); }
; DEV void gemm_tile(const u16* __restrict__ A, const u16* __restrict__ Bt, u16* __restrict__ C, int N, int K,
;                    int brow, int bcol, unsigned char* smem, int epi, const GateEpi& ge) {
;     ...
;         const int R0 = ai * 128 + wr * 64 + m * 16 + fq2 * 4;
; #pragma unroll
;         for (int n = 0; n < 2; ++n) {
;           const int cl = wc * 32 + n * 16 + fr2, cg = pn * 128 + cl;
;           float am2 = 0.f, am1 = 0.f;
;           if (R0 > 0) { am2 = bf2f(sAt[(R0 - 2) * AS + cl]); am1 = bf2f(sAt[(R0 - 1) * AS + cl]); }
; #pragma unroll
;           for (int j = 0; j < 4; ++j) {
;             const float a0 = acc[ai][0][m][n][j], b0 = acc[ai][1][m][n][j];
;             if (R0 > 0 || j >= 2) {
;               const float gv = gelu_tanh(bs[n] + w0[n] * am2 + w1[n] * am1 + w2[n] * a0) * b0;
;               ge.g[(size_t)(brow + R0 + j) * DFF + cg] = f2bf(gv);
;             } else {
;               ge.first_a[((size_t)pm * 2 + j) * DFF + cg] = sAt[(R0 + j) * AS + cl];
;               ge.first_b[((size_t)pm * 2 + j) * DFF + cg] = f2bf(b0);
;             }
;             if (R0 == 252 && j >= 2) ge.halo_a[((size_t)pm * 2 + (j - 2)) * DFF + cg] = sAt[(R0 + j) * AS + cl];
;             am2 = am1; am1 = a0;
	v_fmac_f32_dpp v244, v0, v196 row_shr:1 row_mask:0xf bank_mask:0xf
	v_fmac_f32_dpp v245, v1, v197 row_shr:1 row_mask:0xf bank_mask:0xf
	v_fmac_f32_dpp v246, v2, v198 row_shr:1 row_mask:0xf bank_mask:0xf
	v_fmac_f32_dpp v247, v3, v199 row_shr:1 row_mask:0xf bank_mask:0xf
	v_fmac_f32_dpp v240, v12, v216 row_ror:1 row_mask:0xf bank_mask:0xf
	v_fmac_f32_dpp v241, v13, v217 row_ror:1 row_mask:0xf bank_mask:0xf
	v_fmac_f32_dpp v242, v14, v218 row_ror:1 row_mask:0xf bank_mask:0xf
	v_fmac_f32_dpp v243, v15, v219 row_ror:1 row_mask:0xf bank_mask:0xf
	v_fmac_f32_dpp v244, v8, v220 row_ror:1 row_mask:0xf bank_mask:0xf
	v_fmac_f32_dpp v245, v9, v221 row_ror:1 row_mask:0xf bank_mask:0xf
	v_fmac_f32_dpp v246, v10, v222 row_ror:1 row_mask:0xf bank_mask:0xf
	v_fmac_f32_dpp v247, v11, v223 row_ror:1 row_mask:0xf bank_mask:0xf
	v_fmac_f32_dpp v240, v4, v184 row_shr:2 row_mask:0xf bank_mask:0xf
	v_fmac_f32_dpp v241, v5, v185 row_shr:2 row_mask:0xf bank_mask:0xf
	v_fmac_f32_dpp v242, v6, v186 row_shr:2 row_mask:0xf bank_mask:0xf
	v_fmac_f32_dpp v243, v7, v187 row_shr:2 row_mask:0xf bank_mask:0xf
	v_fmac_f32_dpp v244, v0, v188 row_shr:2 row_mask:0xf bank_mask:0xf
	v_fmac_f32_dpp v245, v1, v189 row_shr:2 row_mask:0xf bank_mask:0xf
	v_fmac_f32_dpp v246, v2, v190 row_shr:2 row_mask:0xf bank_mask:0xf
	v_fmac_f32_dpp v247, v3, v191 row_shr:2 row_mask:0xf bank_mask:0xf
	v_fmac_f32_dpp v240, v12, v224 row_ror:2 row_mask:0xf bank_mask:0xf
	v_fmac_f32_dpp v241, v13, v225 row_ror:2 row_mask:0xf bank_mask:0xf
	v_fmac_f32_dpp v242, v14, v226 row_ror:2 row_mask:0xf bank_mask:0xf
	v_fmac_f32_dpp v243, v15, v227 row_ror:2 row_mask:0xf bank_mask:0xf
	v_fmac_f32_dpp v244, v8, v228 row_ror:2 row_mask:0xf bank_mask:0xf
	v_fmac_f32_dpp v245, v9, v229 row_ror:2 row_mask:0xf bank_mask:0xf
	v_fmac_f32_dpp v246, v10, v230 row_ror:2 row_mask:0xf bank_mask:0xf
	v_fmac_f32_dpp v247, v11, v231 row_ror:2 row_mask:0xf bank_mask:0xf
	v_pk_mul_f32 v[248:249], v[240:241], v[240:241]
	v_pk_mul_f32 v[250:251], v[242:243], v[242:243]
	v_pk_mul_f32 v[182:183], v[244:245], v[244:245]
	v_pk_mul_f32 v[154:155], v[246:247], v[246:247]
	v_pk_fma_f32 v[248:249], v[248:249], s[52:53], v[180:181]
	v_pk_fma_f32 v[250:251], v[250:251], s[52:53], v[180:181]
	v_pk_fma_f32 v[182:183], v[182:183], s[52:53], v[180:181]
	v_pk_fma_f32 v[154:155], v[154:155], s[52:53], v[180:181]
	v_pk_mul_f32 v[248:249], v[240:241], v[248:249]
	v_pk_mul_f32 v[250:251], v[242:243], v[250:251]
	v_pk_mul_f32 v[182:183], v[244:245], v[182:183]
	v_pk_mul_f32 v[154:155], v[246:247], v[154:155]
	v_exp_f32_e32 v248, v248
	v_exp_f32_e32 v249, v249
	v_exp_f32_e32 v250, v250
	v_exp_f32_e32 v251, v251
	v_exp_f32_e32 v182, v182
	v_exp_f32_e32 v183, v183
	v_exp_f32_e32 v154, v154
	v_exp_f32_e32 v155, v155
	v_pk_add_f32 v[248:249], v[248:249], s[94:95]
	v_pk_add_f32 v[250:251], v[250:251], s[94:95]
	v_pk_add_f32 v[182:183], v[182:183], s[94:95]
	v_pk_add_f32 v[154:155], v[154:155], s[94:95]
	v_rcp_f32_e32 v248, v248
	v_rcp_f32_e32 v249, v249
	v_rcp_f32_e32 v250, v250
	v_rcp_f32_e32 v251, v251
	v_rcp_f32_e32 v182, v182
	v_rcp_f32_e32 v183, v183
	v_rcp_f32_e32 v154, v154
	v_rcp_f32_e32 v155, v155
	v_pk_mul_f32 v[240:241], v[240:241], v[248:249]
	v_pk_mul_f32 v[242:243], v[242:243], v[250:251]
	v_pk_mul_f32 v[244:245], v[244:245], v[182:183]
	v_pk_mul_f32 v[246:247], v[246:247], v[154:155]
	v_pk_mul_f32 v[240:241], v[240:241], v[88:89]
	v_pk_mul_f32 v[242:243], v[242:243], v[90:91]
	v_pk_mul_f32 v[244:245], v[244:245], v[92:93]
	v_pk_mul_f32 v[246:247], v[246:247], v[94:95]
	v_cvt_pk_bf16_f32 v248, v240, v241
	v_cvt_pk_bf16_f32 v249, v242, v243
	v_cvt_pk_bf16_f32 v250, v244, v245
	v_cvt_pk_bf16_f32 v251, v246, v247
	global_store_dwordx4 v153, v[248:251], s[0:1] nt
	s_cmp_lg_u32 s34, 1
	s_cbranch_scc1 .Lgate_end_0
	s_mov_b32 exec_lo, 0xc000c000
	s_mov_b32 exec_hi, 0xc000c000
	v_cvt_pk_bf16_f32 v240, v4, v5
	v_cvt_pk_bf16_f32 v241, v6, v7
	v_cvt_pk_bf16_f32 v242, v0, v1
	v_cvt_pk_bf16_f32 v243, v2, v3
	global_store_dwordx4 v153, v[240:243], s[54:55] nt
	s_mov_b64 exec, -1
